# phase X to Y boundary waits only for the batch's 32 compress workgroups (the only producers phase Y consumes)
# speedup vs baseline: 1.1022x; 1.0075x over previous
; __global__ void __launch_bounds__(256, 2) hybrid_megakernel(Params p, int ph_lo, int ph_hi) {
;     ...
;     if (ph + 1 < ph_hi) {
;       if (ph_hi > 1000) cg::this_grid().sync();
;       xcd_barrier(xb);
;     }
.Llb_have:
	s_cmp_lg_u32 s0, 1
	s_cbranch_scc1 .Llb_global
	s_lshr_b32 s1, 0x42108, s52
	s_bitcmp1_b32 s1, 0
	s_cbranch_scc1 .Lxbar
	s_lshr_b32 s1, 0x1ffffc, s52
	s_bitcmp1_b32 s1, 0
	s_cbranch_scc0 .Llb_global
	s_waitcnt vmcnt(0) lgkmcnt(0)
	s_barrier
	v_cmp_eq_u32_e32 vcc, 0, v210
	s_and_saveexec_b64 s[0:1], vcc
	s_cbranch_execz .Llbar_x
	v_readlane_b32 s6, v255, 58
	v_readlane_b32 s7, v255, 59
	v_mov_b32_e32 v0, 1
	s_nop 3
	global_atomic_add v0, v1, v0, s[6:7] sc0
	s_waitcnt vmcnt(0)
	v_readfirstlane_b32 s8, v0
	s_lshr_b32 s9, s8, 6
	s_and_b32 s8, s8, 63
	s_cmp_lg_u32 s8, 63
	s_cbranch_scc1 .Llbar_poll
	v_mov_b32_e32 v0, 1
	global_atomic_add v1, v0, s[6:7] offset:1024
	s_branch .Llbar_acq

; __device__ __forceinline__ unsigned xb_ld(unsigned* p)              { return __hip_atomic_load(p, __ATOMIC_RELAXED, __HIP_MEMORY_SCOPE_AGENT); }
; __device__ __forceinline__ unsigned xb_add(unsigned* p, unsigned v) { return __hip_atomic_fetch_add(p, v, __ATOMIC_RELAXED, __HIP_MEMORY_SCOPE_AGENT); }
; #define XB_SPIN(cond, bar) do { unsigned _sp = 0; while (cond) { __builtin_amdgcn_s_sleep(1); \
;     if ((++_sp & 255u) == 0u) { if (xb_ld(&(bar)[XB_TMO])) break; if (_sp > XB_SPIN_CAP) { atomicAdd(&(bar)[XB_TMO], 1u); break; } } } } while (0)
; __device__ __forceinline__ void xcd_barrier(const XcdBarrier& b) {
;     asm volatile("s_waitcnt vmcnt(0)" ::: "memory");
;     __syncthreads();
;     if (threadIdx.x == 0) {
;         unsigned* bar = b.bar;
;         __builtin_amdgcn_s_waitcnt(0);
;         unsigned nloc = b.st[0], nx = b.st[1];
;         if (nloc == 0u) { xcd_barrier_complete(bar, b.x, nloc, nx); b.st[0] = nloc; b.st[1] = nx; }
;         const unsigned old = xb_add(&bar[XB_XSUB(b.x)], 1u);
;         const unsigned gen = old / nloc;
;         if (old + 1u == (gen + 1u) * nloc) {
;             __builtin_amdgcn_fence(__ATOMIC_RELEASE, "agent");
;             asm volatile("s_waitcnt vmcnt(0)" ::: "memory");
;             const unsigned og = xb_add(&bar[XB_TOP], 1u);
;             const unsigned tg = og / nx;
;             if (og + 1u == (tg + 1u) * nx) xb_add(&bar[XB_TOPGEN], 1u);
;             else XB_SPIN(xb_ld(&bar[XB_TOPGEN]) == tg, bar);
;             __builtin_amdgcn_fence(__ATOMIC_ACQUIRE, "agent");
;             xb_add(&bar[XB_XGEN(b.x)], 1u);
;             asm volatile("s_waitcnt vmcnt(0)" ::: "memory");
;         } else {
;             XB_SPIN(xb_ld(&bar[XB_XGEN(b.x)]) == gen, bar);
;             __builtin_amdgcn_fence(__ATOMIC_ACQUIRE, "agent");
;             asm volatile("s_waitcnt vmcnt(0)" ::: "memory");
;         }
.Lxbar:
	s_waitcnt vmcnt(0) lgkmcnt(0)
	s_barrier
	v_cmp_eq_u32_e32 vcc, 0, v210
	s_and_saveexec_b64 s[0:1], vcc
	s_cbranch_execz .Llbar_x
	v_readlane_b32 s6, v255, 58
	v_readlane_b32 s7, v255, 59
	s_add_i32 s9, s52, 2
	s_mul_i32 s9, s9, 0x3334
	s_lshr_b32 s9, s9, 16
	v_readlane_b32 s8, v253, 0
	s_cmpk_ge_u32 s8, 0x100
	s_cbranch_scc1 .Lxbar_poll
	v_mov_b32_e32 v0, 1
	global_atomic_add v0, v1, v0, s[6:7] offset:64 sc0
	s_waitcnt vmcnt(0)
	v_readfirstlane_b32 s8, v0
	s_and_b32 s8, s8, 31
	s_cmp_lg_u32 s8, 31
	s_cbranch_scc1 .Lxbar_poll
	v_mov_b32_e32 v0, 1
	global_atomic_add v1, v0, s[6:7] offset:1056
	s_branch .Llbar_acq

; __device__ __forceinline__ unsigned xb_ld(unsigned* p)              { return __hip_atomic_load(p, __ATOMIC_RELAXED, __HIP_MEMORY_SCOPE_AGENT); }
; #define XB_SPIN(cond, bar) do { unsigned _sp = 0; while (cond) { __builtin_amdgcn_s_sleep(1); \
;     if ((++_sp & 255u) == 0u) { if (xb_ld(&(bar)[XB_TMO])) break; if (_sp > XB_SPIN_CAP) { atomicAdd(&(bar)[XB_TMO], 1u); break; } } } } while (0)
; __device__ __forceinline__ void xcd_barrier(const XcdBarrier& b) {
;     ...
;         } else {
;             XB_SPIN(xb_ld(&bar[XB_XGEN(b.x)]) == gen, bar);
;             __builtin_amdgcn_fence(__ATOMIC_ACQUIRE, "agent");
;             asm volatile("s_waitcnt vmcnt(0)" ::: "memory");
.Lxbar_p:
	s_sleep 1
	global_load_dword v0, v1, s[6:7] offset:1056 sc1
	s_waitcnt vmcnt(0)
	v_readfirstlane_b32 s18, v0
	s_cmp_ge_u32 s18, s9
	s_cbranch_scc1 .Llbar_acq
	s_add_i32 s8, s8, 1
	s_cmp_lt_u32 s8, 0x100000
	s_cbranch_scc1 .Lxbar_p
	s_branch .Llbar_acq
